# v92 plus attention K-fragment prefetch across the tile barrier and MFMA-first tile head
# speedup vs baseline: 1.0017x; 1.0017x over previous
.LBB0_106:
	v_mov_b32_e32 v14, v0
	v_mov_b32_e32 v15, v0
	s_waitcnt vmcnt(0) lgkmcnt(0)
	s_barrier
	v_mov_b32_e32 v1, v0
	v_mov_b32_e32 v2, v0
	v_mov_b32_e32 v3, v0
	v_mov_b32_e32 v4, v0
	v_mov_b32_e32 v5, v0
	v_mov_b32_e32 v6, v0
	v_mov_b32_e32 v7, v0
	v_mov_b32_e32 v8, v0
	v_mov_b32_e32 v9, v0
	v_mov_b32_e32 v10, v0
	v_mov_b32_e32 v11, v0
	v_mov_b32_e32 v12, v0
	v_mov_b32_e32 v13, v0
	s_lshl_b32 s30, s43, 12
	s_lshl_b32 s44, s48, 7
	v_mov_b64_e32 v[62:63], v[14:15]
	v_mov_b64_e32 v[46:47], v[14:15]
	v_mov_b64_e32 v[30:31], v[14:15]
	s_add_i32 s43, s30, 0xffffff80
	v_add_u32_e32 v153, s44, v171
	v_add_u32_e32 v155, s44, v172
	s_add_i32 s45, s46, 0x80
	s_mov_b32 s50, 2
	s_mov_b32 s51, 1
	s_mov_b32 s53, 0
	v_mov_b32_e32 v157, 0
	v_mov_b32_e32 v159, 0
	v_mov_b32_e32 v96, 0
	v_mov_b32_e32 v97, 0
	v_mov_b32_e32 v98, 0
	v_mov_b32_e32 v99, 0
	v_mov_b32_e32 v100, 0
	v_mov_b32_e32 v101, 0
	v_mov_b32_e32 v102, 0
	v_mov_b32_e32 v103, 0
	v_mov_b32_e32 v104, 0
	v_mov_b32_e32 v105, 0
	v_mov_b32_e32 v106, 0
	v_mov_b32_e32 v107, 0
	v_mov_b32_e32 v108, 0
	v_mov_b32_e32 v109, 0
	v_mov_b32_e32 v110, 0
	v_mov_b32_e32 v111, 0
	v_mov_b64_e32 v[60:61], v[12:13]
	v_mov_b64_e32 v[58:59], v[10:11]
	v_mov_b64_e32 v[56:57], v[8:9]
	v_mov_b64_e32 v[54:55], v[6:7]
	v_mov_b64_e32 v[52:53], v[4:5]
	v_mov_b64_e32 v[50:51], v[2:3]
	v_mov_b64_e32 v[48:49], v[0:1]
	v_mov_b64_e32 v[44:45], v[12:13]
	v_mov_b64_e32 v[42:43], v[10:11]
	v_mov_b64_e32 v[40:41], v[8:9]
	v_mov_b64_e32 v[38:39], v[6:7]
	v_mov_b64_e32 v[36:37], v[4:5]
	v_mov_b64_e32 v[34:35], v[2:3]
	v_mov_b64_e32 v[32:33], v[0:1]
	v_mov_b64_e32 v[28:29], v[12:13]
	v_mov_b64_e32 v[26:27], v[10:11]
	v_mov_b64_e32 v[24:25], v[8:9]
	v_mov_b64_e32 v[22:23], v[6:7]
	v_mov_b64_e32 v[20:21], v[4:5]
	v_mov_b64_e32 v[18:19], v[2:3]
	v_mov_b64_e32 v[16:17], v[0:1]
	s_mov_b32 s52, 0
	s_waitcnt vmcnt(0)
	s_mul_i32 s30, s53, 0x2400
	v_add_u32_e32 v242, s30, v173
	s_mul_i32 s30, s53, 0x4800
	v_add_u32_e32 v243, s30, v174
	s_barrier
	ds_read_b128 v[112:115], v242 offset:0
	ds_read_b128 v[116:119], v242 offset:32
	ds_read_b128 v[120:123], v242 offset:64
	ds_read_b128 v[124:127], v242 offset:96
	s_waitcnt lgkmcnt(0)
	s_mov_b32 s58, 0xff800000
	v_readfirstlane_b32 s30, v191
	s_lshr_b32 s30, s30, 8
	s_cmp_eq_u32 s30, 0
	s_cbranch_scc1 .Latt_diff_p0
	s_setprio 1

.Latt_diff_dmaend:
	v_mfma_f32_32x32x16_bf16 v[64:79], v[120:123], v[138:141], v[64:79]
	ds_read_b128 v[120:123], v242 offset:4672
	v_mfma_f32_32x32x16_bf16 v[64:79], v[124:127], v[142:145], v[64:79]
	ds_read_b128 v[124:127], v242 offset:4704
	s_waitcnt lgkmcnt(2)
	v_mfma_f32_32x32x16_bf16 v[80:95], v[112:115], v[130:133], v[96:111]
	v_mfma_f32_32x32x16_bf16 v[80:95], v[116:119], v[134:137], v[80:95]
	s_waitcnt lgkmcnt(0)
	v_mfma_f32_32x32x16_bf16 v[80:95], v[120:123], v[138:141], v[80:95]
	v_mfma_f32_32x32x16_bf16 v[80:95], v[124:127], v[142:145], v[80:95]
	ds_read_b128 v[112:115], v243 offset:27648
	ds_read_b128 v[116:119], v243 offset:32256
	ds_read_b128 v[120:123], v243 offset:36864
	ds_read_b128 v[124:127], v243 offset:41472
	s_nop 0
	v_max3_f32 v227, v64, v65, v66
	v_max3_f32 v228, v67, v68, v69
	v_max3_f32 v227, v227, v70, v71
	v_max3_f32 v228, v228, v72, v73
	v_max3_f32 v227, v227, v74, v75
	v_max3_f32 v228, v228, v76, v77
	v_max3_f32 v227, v227, v78, v79
	v_max3_f32 v229, v80, v81, v82
	v_max3_f32 v226, v83, v84, v85
	v_max3_f32 v229, v229, v86, v87
	v_max3_f32 v226, v226, v88, v89
	v_max3_f32 v229, v229, v90, v91
	v_max3_f32 v226, v226, v92, v93
	v_max3_f32 v229, v229, v94, v95
	v_max3_f32 v226, v226, v227, v228
	v_max_f32_e32 v226, v226, v229
	v_cmp_lt_f32_e32 vcc, s58, v226
	s_cbranch_vccnz .Latt_diff_rare

.Latt_diff_dmax:
	s_add_i32 m0, s55, 0xac00
	s_and_b64 vcc, exec, s[8:9]
	global_load_lds_dwordx4 v146, s[30:31]
	s_cbranch_vccnz .Latt_diff_dmaend
	s_add_i32 m0, s56, 0x2000
	v_lshl_add_u32 v244, s48, 12, v155
	global_load_lds_dwordx4 v244, s[18:19]
	s_branch .Latt_diff_dmaend
.Latt_diff_rare:
	s_cmp_eq_u32 s52, 0
	s_cselect_b32 s31, 0xff7fffff, 0
	s_mov_b32 s58, 0x41000000
	v_mov_b32_e32 v227, v226
	s_nop 1
	v_permlane32_swap_b32_e32 v226, v227
	v_max_f32_e32 v237, v226, v227
	v_max_f32_e32 v238, s31, v237
	v_max_f32_e32 v239, 0, v238
	v_add_f32_e32 v159, v159, v238
	v_exp_f32_e64 v240, -v239
	v_sub_f32_e32 v96, v96, v238
	v_mov_b32_e32 v97, v96
	v_mov_b32_e32 v98, v96
	v_mov_b32_e32 v99, v96
	v_mov_b32_e32 v100, v96
	v_mov_b32_e32 v101, v96
	v_mov_b32_e32 v102, v96
	v_mov_b32_e32 v103, v96
	v_mov_b32_e32 v104, v96
	v_mov_b32_e32 v105, v96
	v_mov_b32_e32 v106, v96
	v_mov_b32_e32 v107, v96
	v_mov_b32_e32 v108, v96
	v_mov_b32_e32 v109, v96
	v_mov_b32_e32 v110, v96
	v_mov_b32_e32 v111, v96
	v_sub_f32_e32 v64, v64, v238
	v_sub_f32_e32 v65, v65, v238
	v_sub_f32_e32 v66, v66, v238
	v_sub_f32_e32 v67, v67, v238
	v_sub_f32_e32 v68, v68, v238
	v_sub_f32_e32 v69, v69, v238
	v_sub_f32_e32 v70, v70, v238
	v_sub_f32_e32 v71, v71, v238
	v_sub_f32_e32 v72, v72, v238
	v_sub_f32_e32 v73, v73, v238
	v_sub_f32_e32 v74, v74, v238
	v_sub_f32_e32 v75, v75, v238
	v_sub_f32_e32 v76, v76, v238
	v_sub_f32_e32 v77, v77, v238
	v_sub_f32_e32 v78, v78, v238
	v_sub_f32_e32 v79, v79, v238
	v_sub_f32_e32 v80, v80, v238
	v_sub_f32_e32 v81, v81, v238
	v_sub_f32_e32 v82, v82, v238
	v_sub_f32_e32 v83, v83, v238
	v_sub_f32_e32 v84, v84, v238
	v_sub_f32_e32 v85, v85, v238
	v_sub_f32_e32 v86, v86, v238
	v_sub_f32_e32 v87, v87, v238
	v_sub_f32_e32 v88, v88, v238
	v_sub_f32_e32 v89, v89, v238
	v_sub_f32_e32 v90, v90, v238
	v_sub_f32_e32 v91, v91, v238
	v_sub_f32_e32 v92, v92, v238
	v_sub_f32_e32 v93, v93, v238
	v_sub_f32_e32 v94, v94, v238
	v_sub_f32_e32 v95, v95, v238
	v_mul_f32_e32 v157, v157, v240
	v_pk_mul_f32 v[0:1], v[0:1], v[240:241] op_sel_hi:[1,0]
	v_pk_mul_f32 v[2:3], v[2:3], v[240:241] op_sel_hi:[1,0]
	v_pk_mul_f32 v[4:5], v[4:5], v[240:241] op_sel_hi:[1,0]
	v_pk_mul_f32 v[6:7], v[6:7], v[240:241] op_sel_hi:[1,0]
	v_pk_mul_f32 v[8:9], v[8:9], v[240:241] op_sel_hi:[1,0]
	v_pk_mul_f32 v[10:11], v[10:11], v[240:241] op_sel_hi:[1,0]
	v_pk_mul_f32 v[12:13], v[12:13], v[240:241] op_sel_hi:[1,0]
	v_pk_mul_f32 v[14:15], v[14:15], v[240:241] op_sel_hi:[1,0]
	v_pk_mul_f32 v[48:49], v[48:49], v[240:241] op_sel_hi:[1,0]
	v_pk_mul_f32 v[50:51], v[50:51], v[240:241] op_sel_hi:[1,0]
	v_pk_mul_f32 v[52:53], v[52:53], v[240:241] op_sel_hi:[1,0]
	v_pk_mul_f32 v[54:55], v[54:55], v[240:241] op_sel_hi:[1,0]
	v_pk_mul_f32 v[56:57], v[56:57], v[240:241] op_sel_hi:[1,0]
	v_pk_mul_f32 v[58:59], v[58:59], v[240:241] op_sel_hi:[1,0]
	v_pk_mul_f32 v[60:61], v[60:61], v[240:241] op_sel_hi:[1,0]
	v_pk_mul_f32 v[62:63], v[62:63], v[240:241] op_sel_hi:[1,0]
	v_pk_mul_f32 v[32:33], v[32:33], v[240:241] op_sel_hi:[1,0]
	v_pk_mul_f32 v[34:35], v[34:35], v[240:241] op_sel_hi:[1,0]
	v_pk_mul_f32 v[36:37], v[36:37], v[240:241] op_sel_hi:[1,0]
	v_pk_mul_f32 v[38:39], v[38:39], v[240:241] op_sel_hi:[1,0]
	v_pk_mul_f32 v[40:41], v[40:41], v[240:241] op_sel_hi:[1,0]
	v_pk_mul_f32 v[42:43], v[42:43], v[240:241] op_sel_hi:[1,0]
	v_pk_mul_f32 v[44:45], v[44:45], v[240:241] op_sel_hi:[1,0]
	v_pk_mul_f32 v[46:47], v[46:47], v[240:241] op_sel_hi:[1,0]
	v_pk_mul_f32 v[16:17], v[16:17], v[240:241] op_sel_hi:[1,0]
	v_pk_mul_f32 v[18:19], v[18:19], v[240:241] op_sel_hi:[1,0]
	v_pk_mul_f32 v[20:21], v[20:21], v[240:241] op_sel_hi:[1,0]
	v_pk_mul_f32 v[22:23], v[22:23], v[240:241] op_sel_hi:[1,0]
	v_pk_mul_f32 v[24:25], v[24:25], v[240:241] op_sel_hi:[1,0]
	v_pk_mul_f32 v[26:27], v[26:27], v[240:241] op_sel_hi:[1,0]
	v_pk_mul_f32 v[28:29], v[28:29], v[240:241] op_sel_hi:[1,0]
	v_pk_mul_f32 v[30:31], v[30:31], v[240:241] op_sel_hi:[1,0]
	s_branch .Latt_diff_norescale

.LBB0_177:
	v_mov_b32_e32 v14, v0
	v_mov_b32_e32 v15, v0
	s_waitcnt vmcnt(0) lgkmcnt(0)
	s_barrier
	v_mov_b32_e32 v1, v0
	v_mov_b32_e32 v2, v0
	v_mov_b32_e32 v3, v0
	v_mov_b32_e32 v4, v0
	v_mov_b32_e32 v5, v0
	v_mov_b32_e32 v6, v0
	v_mov_b32_e32 v7, v0
	v_mov_b32_e32 v8, v0
	v_mov_b32_e32 v9, v0
	v_mov_b32_e32 v10, v0
	v_mov_b32_e32 v11, v0
	v_mov_b32_e32 v12, v0
	v_mov_b32_e32 v13, v0
	s_lshl_b32 s49, s49, 12
	v_mov_b64_e32 v[30:31], v[14:15]
	v_mov_b64_e32 v[46:47], v[14:15]
	v_mov_b64_e32 v[62:63], v[14:15]
	v_mad_u64_u32 v[222:223], s[30:31], s50, v238, v[190:191]
	v_mad_u64_u32 v[224:225], s[30:31], s50, v240, v[192:193]
	v_mad_u64_u32 v[226:227], s[30:31], s50, v242, v[194:195]
	v_mad_u64_u32 v[228:229], s[30:31], s50, v244, v[196:197]
	s_addk_i32 s49, 0xff80
	s_add_i32 s51, s60, 0x80
	s_mov_b32 s52, 2
	s_mov_b32 s53, 1
	s_mov_b32 s56, 0
	v_mov_b32_e32 v205, 0
	v_mov_b32_e32 v207, 0
	v_mov_b32_e32 v96, 0
	v_mov_b32_e32 v97, 0
	v_mov_b32_e32 v98, 0
	v_mov_b32_e32 v99, 0
	v_mov_b32_e32 v100, 0
	v_mov_b32_e32 v101, 0
	v_mov_b32_e32 v102, 0
	v_mov_b32_e32 v103, 0
	v_mov_b32_e32 v104, 0
	v_mov_b32_e32 v105, 0
	v_mov_b32_e32 v106, 0
	v_mov_b32_e32 v107, 0
	v_mov_b32_e32 v108, 0
	v_mov_b32_e32 v109, 0
	v_mov_b32_e32 v110, 0
	v_mov_b32_e32 v111, 0
	v_mov_b64_e32 v[28:29], v[12:13]
	v_mov_b64_e32 v[26:27], v[10:11]
	v_mov_b64_e32 v[24:25], v[8:9]
	v_mov_b64_e32 v[22:23], v[6:7]
	v_mov_b64_e32 v[20:21], v[4:5]
	v_mov_b64_e32 v[18:19], v[2:3]
	v_mov_b64_e32 v[16:17], v[0:1]
	v_mov_b64_e32 v[44:45], v[12:13]
	v_mov_b64_e32 v[42:43], v[10:11]
	v_mov_b64_e32 v[40:41], v[8:9]
	v_mov_b64_e32 v[38:39], v[6:7]
	v_mov_b64_e32 v[36:37], v[4:5]
	v_mov_b64_e32 v[34:35], v[2:3]
	v_mov_b64_e32 v[32:33], v[0:1]
	v_mov_b64_e32 v[60:61], v[12:13]
	v_mov_b64_e32 v[58:59], v[10:11]
	v_mov_b64_e32 v[56:57], v[8:9]
	v_mov_b64_e32 v[54:55], v[6:7]
	v_mov_b64_e32 v[52:53], v[4:5]
	v_mov_b64_e32 v[50:51], v[2:3]
	v_mov_b64_e32 v[48:49], v[0:1]
	s_mov_b32 s55, 0
	s_waitcnt vmcnt(0)
	s_mul_i32 s30, s56, 0x6400
	v_add_u32_e32 v217, s30, v246
	s_mul_i32 s30, s56, 0x4800
	v_add_u32_e32 v219, s30, v247
	s_barrier
	ds_read_b128 v[112:115], v217 offset:0
	ds_read_b128 v[116:119], v217 offset:32
	ds_read_b128 v[120:123], v217 offset:64
	ds_read_b128 v[124:127], v217 offset:96
	ds_read_b128 v[250:253], v217 offset:128
	s_waitcnt lgkmcnt(0)
	s_mov_b32 s58, 0xff800000
	v_readfirstlane_b32 s30, v191
	s_lshr_b32 s30, s30, 8
	s_cmp_eq_u32 s30, 0
	s_cbranch_scc1 .Latt_mla_p0
	s_setprio 1

.Latt_mla_dmaend:
	v_mfma_f32_32x32x16_bf16 v[64:79], v[120:123], v[138:141], v[64:79]
	ds_read_b128 v[120:123], v217 offset:224
	v_mfma_f32_32x32x16_bf16 v[64:79], v[124:127], v[142:145], v[64:79]
	ds_read_b128 v[124:127], v217 offset:256
	v_mfma_f32_32x32x16_bf16 v[64:79], v[250:253], v[146:149], v[64:79]
	ds_read_b128 v[250:253], v217 offset:288
	s_waitcnt lgkmcnt(3)
	v_mfma_f32_32x32x16_bf16 v[64:79], v[112:115], v[150:153], v[64:79]
	ds_read_b128 v[112:115], v217 offset:320
	v_mfma_f32_32x32x16_bf16 v[64:79], v[116:119], v[154:157], v[64:79]
	ds_read_b128 v[116:119], v217 offset:352
	s_waitcnt lgkmcnt(3)
	v_mfma_f32_32x32x16_bf16 v[64:79], v[120:123], v[158:161], v[64:79]
	ds_read_b128 v[120:123], v217 offset:12800
	v_mfma_f32_32x32x16_bf16 v[64:79], v[124:127], v[162:165], v[64:79]
	ds_read_b128 v[124:127], v217 offset:12832
	s_waitcnt lgkmcnt(3)
	v_mfma_f32_32x32x16_bf16 v[64:79], v[250:253], v[166:169], v[64:79]
	ds_read_b128 v[250:253], v217 offset:12864
	v_mfma_f32_32x32x16_bf16 v[64:79], v[112:115], v[170:173], v[64:79]
	ds_read_b128 v[112:115], v217 offset:12896
	s_waitcnt lgkmcnt(3)
	v_mfma_f32_32x32x16_bf16 v[64:79], v[116:119], v[174:177], v[64:79]
	ds_read_b128 v[116:119], v217 offset:12928
	v_mfma_f32_32x32x16_bf16 v[80:95], v[120:123], v[130:133], v[96:111]
	ds_read_b128 v[120:123], v217 offset:12960
	s_waitcnt lgkmcnt(3)
	v_mfma_f32_32x32x16_bf16 v[80:95], v[124:127], v[134:137], v[80:95]
	ds_read_b128 v[124:127], v217 offset:12992
	v_mfma_f32_32x32x16_bf16 v[80:95], v[250:253], v[138:141], v[80:95]
	ds_read_b128 v[250:253], v217 offset:13024
	s_waitcnt lgkmcnt(3)
	v_mfma_f32_32x32x16_bf16 v[80:95], v[112:115], v[142:145], v[80:95]
	ds_read_b128 v[112:115], v217 offset:13056
	v_mfma_f32_32x32x16_bf16 v[80:95], v[116:119], v[146:149], v[80:95]
	ds_read_b128 v[116:119], v217 offset:13088
	v_max3_f32 v211, v64, v65, v66
	s_waitcnt lgkmcnt(3)
	v_mfma_f32_32x32x16_bf16 v[80:95], v[120:123], v[150:153], v[80:95]
	ds_read_b128 v[120:123], v217 offset:13120
	v_max3_f32 v213, v67, v68, v69
	v_mfma_f32_32x32x16_bf16 v[80:95], v[124:127], v[154:157], v[80:95]
	ds_read_b128 v[124:127], v217 offset:13152
	v_max3_f32 v211, v211, v70, v71
	s_waitcnt lgkmcnt(3)
	v_mfma_f32_32x32x16_bf16 v[80:95], v[250:253], v[158:161], v[80:95]
	v_max3_f32 v213, v213, v72, v73
	v_mfma_f32_32x32x16_bf16 v[80:95], v[112:115], v[162:165], v[80:95]
	v_max3_f32 v211, v211, v74, v75
	s_waitcnt lgkmcnt(1)
	v_mfma_f32_32x32x16_bf16 v[80:95], v[116:119], v[166:169], v[80:95]
	v_max3_f32 v213, v213, v76, v77
	v_mfma_f32_32x32x16_bf16 v[80:95], v[120:123], v[170:173], v[80:95]
	v_max3_f32 v211, v211, v78, v79
	s_waitcnt lgkmcnt(0)
	v_mfma_f32_32x32x16_bf16 v[80:95], v[124:127], v[174:177], v[80:95]
	ds_read_b128 v[112:115], v219 offset:0
	ds_read_b128 v[116:119], v219 offset:4608
	ds_read_b128 v[120:123], v219 offset:9216
	s_nop 8
	v_max3_f32 v215, v80, v81, v82
	v_max3_f32 v209, v83, v84, v85
	v_max3_f32 v215, v215, v86, v87
	v_max3_f32 v209, v209, v88, v89
	v_max3_f32 v215, v215, v90, v91
	v_max3_f32 v209, v209, v92, v93
	v_max3_f32 v215, v215, v94, v95
	v_max3_f32 v209, v209, v211, v213
	v_max_f32_e32 v209, v209, v215
	v_cmp_lt_f32_e32 vcc, s58, v209
	s_cbranch_vccnz .Latt_mla_rare
